# nt on the read-once f32 x loads of the P0 conversion loop
# speedup vs baseline: 1.0043x; 1.0043x over previous
; __device__ __forceinline__ unsigned cvt_pk_bf16(float lo, float hi) { unsigned r; asm volatile("v_cvt_pk_bf16_f32 %0, %1, %2" : "=v"(r) : "v"(lo), "v"(hi)); return r; }
; __device__ __forceinline__ void p0_prologue(const Ptrs& P, unsigned char* lds, int tid, int G) {
;     ...
; #pragma unroll 4
;     for (size_t i = gt; i < (size_t)M * D / 8; i += GT) { const f32x4 a = *(const f32x4*)(P.x + i * 8), b = *(const f32x4*)(P.x + i * 8 + 4);
;         u32x4 w; w.x = cvt_pk_bf16(a[0], a[1]); w.y = cvt_pk_bf16(a[2], a[3]); w.z = cvt_pk_bf16(b[0], b[1]); w.w = cvt_pk_bf16(b[2], b[3]); *(u32x4*)(P.XB + i * 8) = w; }
.LBB0_103:
	global_load_dwordx4 v[10:13], v[8:9], off offset:-16 nt
	global_load_dwordx4 v[14:17], v[8:9], off nt
	v_lshl_add_u64 v[6:7], v[6:7], 0, s[0:1]
	v_cmp_lt_u64_e32 vcc, s[14:15], v[6:7]
	v_lshl_add_u64 v[8:9], v[8:9], 0, s[8:9]
	s_or_b64 s[12:13], vcc, s[12:13]
	s_waitcnt vmcnt(1)
	v_cvt_pk_bf16_f32 v10, v10, v11
	v_cvt_pk_bf16_f32 v11, v12, v13
	s_waitcnt vmcnt(0)
	v_cvt_pk_bf16_f32 v12, v14, v15
	v_cvt_pk_bf16_f32 v13, v16, v17
	global_store_dwordx4 v[4:5], v[10:13], off
	v_lshl_add_u64 v[4:5], v[4:5], 0, s[10:11]
	s_andn2_b64 exec, exec, s[12:13]
	s_cbranch_execnz .LBB0_103
